# wt1 + P3 tile-type permutation v2 (2<->4, 3<->12, 1<->16, 9<->20): six-unit workgroups get raw/silu epilogues
# speedup vs baseline: 1.0055x; 1.0015x over previous
.LBB0_777:
	s_or_b64 exec, exec, s[0:1]
	v_mov_b32_e32 v9, v0
	v_cndmask_b32_e64 v1, 0, 1, s[20:21]
	s_waitcnt lgkmcnt(0)
	s_barrier
	v_cmp_ne_u32_e64 s[0:1], 1, v1
	s_andn2_b64 vcc, exec, s[20:21]
	v_readfirstlane_b32 s4, v9
	s_cbranch_vccnz .LBB0_779
	s_lshr_b32 s5, s30, 29
	s_add_i32 s5, s2, s5
	s_ashr_i32 s6, s5, 3
	s_and_b32 s5, s5, -8
	s_sub_i32 s5, s2, s5
	s_cmp_lt_i32 s5, 0
	s_movk_i32 s7, 0xa9
	s_cselect_b32 s7, s7, 0xa8
	s_mul_i32 s5, s5, s7
	s_add_i32 s5, s5, s6
	s_mul_hi_i32 s6, s5, 0x30c30c31
	s_lshr_b32 s7, s6, 31
	s_ashr_i32 s6, s6, 5
	s_add_i32 s6, s6, s7
	s_lshl_b32 s7, s6, 3
	s_mulk_i32 s6, 0xa8
	s_sub_i32 s5, s5, s6
	s_sext_i32_i16 s6, s5
	s_bfe_u32 s6, s6, 0x3001c
	s_add_i32 s6, s5, s6
	s_sext_i32_i16 s8, s6
	s_and_b32 s6, s6, 0xfff8
	s_sub_i32 s5, s5, s6
	s_sext_i32_i16 s5, s5
	s_add_i32 s6, s7, s5
	s_ashr_i32 s76, s8, 3
	s_mov_b32 s32, s76
	s_cmp_eq_u32 s76, 2
	s_cselect_b32 s32, 4, s32
	s_cmp_eq_u32 s76, 4
	s_cselect_b32 s32, 2, s32
	s_cmp_eq_u32 s76, 3
	s_cselect_b32 s32, 12, s32
	s_cmp_eq_u32 s76, 12
	s_cselect_b32 s32, 3, s32
	s_cmp_eq_u32 s76, 1
	s_cselect_b32 s32, 16, s32
	s_cmp_eq_u32 s76, 16
	s_cselect_b32 s32, 1, s32
	s_cmp_eq_u32 s76, 9
	s_cselect_b32 s32, 20, s32
	s_cmp_eq_u32 s76, 20
	s_cselect_b32 s32, 9, s32
	s_mov_b32 s76, s32

.LBB0_787:
	v_add_u32_e32 v202, 0, v205
	v_add_u32_e32 v236, 0x10000, v202
	v_add_u32_e32 v237, 0x14000, v202
	ds_read_b128 v[146:149], v236
	ds_read_b128 v[150:153], v236 offset:1024
	ds_read_b128 v[154:157], v236 offset:2048
	ds_read_b128 v[158:161], v236 offset:3072
	ds_read_b128 v[130:133], v237
	ds_read_b128 v[134:137], v237 offset:1024
	ds_read_b128 v[138:141], v237 offset:2048
	ds_read_b128 v[142:145], v237 offset:3072
	s_add_i32 s42, s42, 1
	v_lshl_add_u64 v[220:221], s[78:79], 0, v[194:195]
	s_add_i32 s0, s77, 0x8000
	v_lshl_add_u64 v[222:223], v[220:221], 0, s[36:37]
	s_mov_b32 m0, s0
	s_add_i32 s7, s77, 0xa000
	ds_read_b128 v[186:189], v235
	ds_read_b128 v[190:193], v235 offset:1024
	ds_read_b128 v[178:181], v235 offset:2048
	ds_read_b128 v[182:185], v235 offset:3072
	ds_read_b128 v[170:173], v235 offset:4096
	ds_read_b128 v[174:177], v235 offset:5120
	ds_read_b128 v[162:165], v235 offset:6144
	ds_read_b128 v[166:169], v235 offset:7168
	global_load_lds_dwordx4 v[222:223], off
	v_lshl_add_u64 v[222:223], s[78:79], 0, v[198:199]
	s_add_u32 s4, s78, 0x40080
	v_lshl_add_u64 v[224:225], v[222:223], 0, s[36:37]
	s_mov_b32 m0, s7
	s_addc_u32 s5, s79, 0
	s_add_i32 s57, s77, 0xc000
	global_load_lds_dwordx4 v[224:225], off
	v_lshl_add_u64 v[224:225], s[4:5], 0, v[194:195]
	s_mov_b32 m0, s57
	s_add_i32 s58, s77, 0xe000
	global_load_lds_dwordx4 v[224:225], off
	v_lshl_add_u64 v[224:225], s[4:5], 0, v[198:199]
	s_mov_b32 m0, s58
	s_nop 0
	global_load_lds_dwordx4 v[224:225], off
	s_mul_i32 s4, s42, s43
	s_mul_hi_u32 s5, s42, s3
	s_add_i32 s5, s5, s4
	s_mul_i32 s4, s42, s3
	s_add_u32 s28, s4, s2
	s_addc_u32 s29, s5, s30
	v_cmp_gt_i64_e32 vcc, s[28:29], v[218:219]
	v_cmp_lt_i64_e64 s[4:5], s[28:29], v[216:217]
	s_cbranch_vccnz .LBB0_789
	s_ashr_i32 s12, s28, 31
	s_lshr_b32 s12, s12, 29
	s_add_i32 s12, s28, s12
	s_ashr_i32 s16, s12, 3
	s_and_b32 s12, s12, -8
	s_sub_i32 s12, s28, s12
	s_cmp_lt_i32 s12, 0
	s_movk_i32 s17, 0xa9
	s_cselect_b32 s17, s17, 0xa8
	s_mul_i32 s12, s12, s17
	s_add_i32 s12, s12, s16
	s_mul_hi_i32 s16, s12, 0x30c30c31
	s_lshr_b32 s17, s16, 31
	s_ashr_i32 s16, s16, 5
	s_add_i32 s16, s16, s17
	s_lshl_b32 s17, s16, 3
	s_mulk_i32 s16, 0xa8
	s_sub_i32 s12, s12, s16
	s_bfe_u32 s16, s12, 0x3001c
	s_add_i32 s16, s12, s16
	s_sext_i32_i16 s18, s16
	s_and_b32 s16, s16, 0xfff8
	s_sub_i32 s12, s12, s16
	s_sext_i32_i16 s12, s12
	s_add_i32 s72, s17, s12
	s_ashr_i32 s74, s18, 3
	s_mov_b32 s32, s74
	s_cmp_eq_u32 s74, 2
	s_cselect_b32 s32, 4, s32
	s_cmp_eq_u32 s74, 4
	s_cselect_b32 s32, 2, s32
	s_cmp_eq_u32 s74, 3
	s_cselect_b32 s32, 12, s32
	s_cmp_eq_u32 s74, 12
	s_cselect_b32 s32, 3, s32
	s_cmp_eq_u32 s74, 1
	s_cselect_b32 s32, 16, s32
	s_cmp_eq_u32 s74, 16
	s_cselect_b32 s32, 1, s32
	s_cmp_eq_u32 s74, 9
	s_cselect_b32 s32, 20, s32
	s_cmp_eq_u32 s74, 20
	s_cselect_b32 s32, 9, s32
	s_mov_b32 s74, s32
	s_mov_b32 s12, s42
